# stack + half the workgroups (bid bit3) delayed ~8us at in_proj (p1) entry so the VALU-bound epilogues of one half overlap the K-loops of the other
# baseline (speedup 1.0000x reference)
;     __device__ bool next(int i, Unit& u) const {
;         const int nr = (nwg + G - 1) / G; if (i >= nr) return false;
;         const long L = (long)(rev ? nr - 1 - i : i) * G + c; if (L >= nwg) return false;
;         int wgid = (int)L; { const int q = nwg / NXCD, r = nwg % NXCD, xcd = wgid % NXCD, off = wgid / NXCD; wgid = (xcd < r ? xcd * (q + 1) : r * (q + 1) + (xcd - r) * q) + off; }
;         const int nig = WGM * nN, gid = wgid / nig, fm = gid * WGM, gsz = (nM - fm) < WGM ? (nM - fm) : WGM;
;         u.pm = fm + ((wgid % nig) % gsz); u.pn = (wgid % nig) / gsz; return true;
; __global__ void __launch_bounds__(512, 2) fwd_kernel(Params p) {
;     ...
;         case 1: {
;             { pg8::Gemm g{TB, Wt_in, M, NIN, D, nullptr, nullptr}; pg8::StaticOrder S; S.init(M, NIN, G, bid);
;               EpiIn E{GU, GV, QB, KB, VB, SA, SB, p.in[z0 + 3] + (size_t)l * 2 * D, ROPE, STATSV, Fold{l == 0 ? (const float*)nullptr : STP, CSB + CS_IN, NIN}};
;               pg8::gemm_phase<EpiIn>(lds, g, S, E, tid); }
.LBB0_528:
	s_andn2_b64 vcc, exec, s[0:1]
	s_cbranch_vccnz .LBB0_27
	v_readlane_b32 s0, v251, 28
	s_bitcmp1_b32 s0, 3
	s_cbranch_scc0 .Lstag_skip_p1
	s_sleep 127
	s_sleep 127
.Lstag_skip_p1:
	s_add_u32 s8, s42, 0x3000000
	s_addc_u32 s9, s43, 0
	s_add_u32 s4, s42, 0x20703600
	s_addc_u32 s5, s43, 0
	v_readlane_b32 s0, v252, 8
	s_cmp_gt_i32 s0, 0
	s_mov_b64 s[0:1], -1
	s_cbranch_scc0 .LBB0_884
	v_readlane_b32 s0, v251, 29
	v_readlane_b32 s1, v251, 30
	s_mov_b32 s6, s0
	s_ashr_i32 s7, s0, 31
	v_writelane_b32 v251, s0, 29
	v_readlane_b32 s10, v250, 48
	v_readlane_b32 s11, v250, 49
	v_writelane_b32 v251, s1, 30
	s_lshl_b64 s[0:1], s[6:7], 3
	s_add_u32 s6, s68, s0
	s_addc_u32 s7, s69, s1
	v_readlane_b32 s0, v251, 28
	s_cmpk_lt_i32 s0, 0x780
	s_cselect_b64 s[0:1], -1, 0
	s_and_b64 s[10:11], s[10:11], s[0:1]
	v_cndmask_b32_e64 v0, 0, 1, s[10:11]
	v_cmp_ne_u32_e64 s[0:1], 1, v0
	s_andn2_b64 vcc, exec, s[10:11]
	v_readfirstlane_b32 s2, v210
	s_cbranch_vccnz .LBB0_532
	v_readlane_b32 s12, v251, 28
	s_ashr_i32 s10, s12, 31
	s_lshr_b32 s10, s10, 29
	s_add_i32 s10, s12, s10
	s_ashr_i32 s11, s10, 3
	s_and_b32 s10, s10, -8
	s_sub_i32 s10, s12, s10
	s_cmp_lt_i32 s10, 0
	s_movk_i32 s12, 0xf1
	s_cselect_b32 s12, s12, 0xf0
	s_mul_i32 s10, s10, s12
	s_add_i32 s10, s10, s11
	s_mul_hi_i32 s11, s10, 0x88888889
	s_add_i32 s11, s11, s10
	s_lshr_b32 s12, s11, 31
	s_ashr_i32 s11, s11, 6
	s_add_i32 s11, s11, s12
	s_lshl_b32 s12, s11, 2
	s_mulk_i32 s11, 0x78
	s_sub_i32 s10, s10, s11
	s_bfe_i32 s11, s10, 0x80000
	s_bfe_u32 s11, s11, 0x2000d
	s_add_i32 s11, s10, s11
	s_and_b32 s13, s11, 0xfc
	s_sub_i32 s10, s10, s13
	s_sext_i32_i8 s10, s10
	s_add_i32 s30, s12, s10
	s_bfe_i32 s10, s11, 0x80000
	s_sext_i32_i16 s10, s10
	s_ashr_i32 s36, s10, 2
